# prep_a_prompt layernorm-stats loop: the 8 row loads of each iteration hoisted to the loop top (prefetch registers + v_mov), counted vmcnt waits
# speedup vs baseline: 1.0046x; 1.0019x over previous
; DI float gelu_t(float x) { return x * sigm(1.5957691216057308f * (x + 0.044715f * x * x * x)); }
; DI void prep_a_prompt(LAS unsigned char* lds, const Params& P, int l, int unit) {
;     ...
; #pragma unroll 8
;     for (int i = 0; i < 16; ++i) { const int t = wave * 16 + i; const float* p = P32 + (size_t)(row0 + t) * LDP + C_AV + lane * 8;
;         const f32x4 a = *(const f32x4*)p, bq = *(const f32x4*)(p + 4); float x[8];
; #pragma unroll
;         for (int e = 0; e < 4; ++e) { x[e] = gelu_t(a[e]); x[4 + e] = gelu_t(bq[e]); }
;         float s = 0.f;
; #pragma unroll
;         for (int e = 0; e < 8; ++e) s += x[e];
;         const float mean = wsum(s) * (1.f / 512.f); float d = 0.f;
; #pragma unroll
;         for (int e = 0; e < 8; ++e) d += (x[e] - mean) * (x[e] - mean);
;         const float var = wsum(d) * (1.f / 512.f);
;         if (lane == 0) { st[t * 2] = mean; st[t * 2 + 1] = rsqrtf(var + 1e-6f); } }
.LBB0_752:
	v_lshl_add_u64 v[4:5], v[2:3], 0, s[54:55]
	s_mov_b32 s11, 0
	s_mov_b32 s10, 0x0
	v_lshl_add_u64 v[120:121], v[4:5], 0, s[10:11]
	global_load_dwordx4 v[56:59], v[120:121], off offset:2048
	global_load_dwordx4 v[60:63], v[120:121], off offset:2064
	s_mov_b32 s10, 0x6800
	v_lshl_add_u64 v[120:121], v[4:5], 0, s[10:11]
	global_load_dwordx4 v[64:67], v[120:121], off offset:2048
	global_load_dwordx4 v[68:71], v[120:121], off offset:2064
	s_mov_b32 s10, 0xd000
	v_lshl_add_u64 v[120:121], v[4:5], 0, s[10:11]
	global_load_dwordx4 v[72:75], v[120:121], off offset:2048
	global_load_dwordx4 v[76:79], v[120:121], off offset:2064
	s_mov_b32 s10, 0x13800
	v_lshl_add_u64 v[120:121], v[4:5], 0, s[10:11]
	global_load_dwordx4 v[80:83], v[120:121], off offset:2048
	global_load_dwordx4 v[84:87], v[120:121], off offset:2064
	s_mov_b32 s10, 0x1a000
	v_lshl_add_u64 v[120:121], v[4:5], 0, s[10:11]
	global_load_dwordx4 v[88:91], v[120:121], off offset:2048
	global_load_dwordx4 v[92:95], v[120:121], off offset:2064
	s_mov_b32 s10, 0x20800
	v_lshl_add_u64 v[120:121], v[4:5], 0, s[10:11]
	global_load_dwordx4 v[96:99], v[120:121], off offset:2048
	global_load_dwordx4 v[100:103], v[120:121], off offset:2064
	s_mov_b32 s10, 0x27000
	v_lshl_add_u64 v[120:121], v[4:5], 0, s[10:11]
	global_load_dwordx4 v[104:107], v[120:121], off offset:2048
	global_load_dwordx4 v[108:111], v[120:121], off offset:2064
	s_mov_b32 s10, 0x2d800
	v_lshl_add_u64 v[120:121], v[4:5], 0, s[10:11]
	global_load_dwordx4 v[112:115], v[120:121], off offset:2048
	global_load_dwordx4 v[116:119], v[120:121], off offset:2064
	s_waitcnt vmcnt(15) lgkmcnt(0)
	v_mov_b32_e32 v18, v56
	v_mov_b32_e32 v19, v57
	v_mov_b32_e32 v20, v58
	v_mov_b32_e32 v21, v59
	v_mul_f32_e32 v6, 0x3d372713, v18
	v_mul_f32_e32 v26, 0x3d372713, v19
	v_mul_f32_e32 v6, v18, v6
	v_mul_f32_e32 v28, 0x3d372713, v20
	v_mul_f32_e32 v26, v19, v26
	v_fma_f32 v6, v18, v6, v18
	v_mul_f32_e32 v30, 0x3d372713, v21
	v_mul_f32_e32 v28, v20, v28
	v_fma_f32 v26, v19, v26, v19
	v_mul_f32_e32 v6, 0x3fcc422a, v6
	s_waitcnt vmcnt(14)
	v_mov_b32_e32 v22, v60
	v_mov_b32_e32 v23, v61
	v_mov_b32_e32 v24, v62
	v_mov_b32_e32 v25, v63
	v_mul_f32_e32 v7, 0x3d372713, v22
	v_mul_f32_e32 v30, v21, v30
	v_fma_f32 v28, v20, v28, v20
	v_mul_f32_e32 v26, 0x3fcc422a, v26
	v_mul_f32_e32 v6, 0xbfb8aa3b, v6
	v_mul_f32_e32 v27, 0x3d372713, v23
	v_mul_f32_e32 v7, v22, v7
	v_fma_f32 v30, v21, v30, v21
	v_mul_f32_e32 v28, 0x3fcc422a, v28
	v_mul_f32_e32 v26, 0xbfb8aa3b, v26
	v_exp_f32_e32 v6, v6
	v_mul_f32_e32 v29, 0x3d372713, v24
	v_mul_f32_e32 v27, v23, v27
	v_fma_f32 v7, v22, v7, v22
	v_mul_f32_e32 v30, 0x3fcc422a, v30
	v_mul_f32_e32 v28, 0xbfb8aa3b, v28
	v_exp_f32_e32 v26, v26
	v_mul_f32_e32 v31, 0x3d372713, v25
	v_mul_f32_e32 v29, v24, v29
	v_fma_f32 v27, v23, v27, v23
	v_mul_f32_e32 v7, 0x3fcc422a, v7
	v_mul_f32_e32 v30, 0xbfb8aa3b, v30
	v_exp_f32_e32 v28, v28
	v_mul_f32_e32 v31, v25, v31
	v_fma_f32 v29, v24, v29, v24
	v_mul_f32_e32 v27, 0x3fcc422a, v27
	v_mul_f32_e32 v7, 0xbfb8aa3b, v7
	v_exp_f32_e32 v30, v30
	v_fma_f32 v31, v25, v31, v25
	v_mul_f32_e32 v29, 0x3fcc422a, v29
	v_mul_f32_e32 v27, 0xbfb8aa3b, v27
	v_exp_f32_e32 v7, v7
	v_add_f32_e32 v6, 1.0, v6
	v_mul_f32_e32 v31, 0x3fcc422a, v31
	v_mul_f32_e32 v29, 0xbfb8aa3b, v29
	v_exp_f32_e32 v27, v27
	v_add_f32_e32 v26, 1.0, v26
	v_rcp_f32_e32 v32, v6
	v_mul_f32_e32 v31, 0xbfb8aa3b, v31
	v_exp_f32_e32 v29, v29
	v_add_f32_e32 v28, 1.0, v28
	v_rcp_f32_e32 v26, v26
	v_exp_f32_e32 v31, v31
	v_add_f32_e32 v30, 1.0, v30
	v_rcp_f32_e32 v28, v28
	v_add_f32_e32 v7, 1.0, v7
	v_rcp_f32_e32 v30, v30
	v_add_f32_e32 v27, 1.0, v27
	v_rcp_f32_e32 v7, v7
	v_fma_f32 v6, v18, v32, 0
	v_add_f32_e32 v29, 1.0, v29
	v_rcp_f32_e32 v27, v27
	v_fmac_f32_e32 v6, v19, v26
	v_add_f32_e32 v31, 1.0, v31
	v_rcp_f32_e32 v29, v29
	v_fmac_f32_e32 v6, v20, v28
	v_rcp_f32_e32 v31, v31
	v_fmac_f32_e32 v6, v21, v30
	v_fmac_f32_e32 v6, v22, v7
	v_fmac_f32_e32 v6, v23, v27
	v_fmac_f32_e32 v6, v24, v29
	v_fmac_f32_e32 v6, v25, v31
	ds_bpermute_b32 v33, v9, v6
	s_waitcnt lgkmcnt(0)
	v_add_f32_e32 v6, v6, v33
	ds_bpermute_b32 v33, v10, v6
	s_waitcnt lgkmcnt(0)
	v_add_f32_e32 v6, v6, v33
	ds_bpermute_b32 v33, v11, v6
	s_waitcnt lgkmcnt(0)
	v_add_f32_e32 v6, v6, v33
	ds_bpermute_b32 v33, v12, v6
	s_waitcnt lgkmcnt(0)
	v_add_f32_e32 v6, v6, v33
	ds_bpermute_b32 v33, v13, v6
	s_waitcnt lgkmcnt(0)
	v_add_f32_e32 v6, v6, v33
	ds_bpermute_b32 v33, v16, v6
	s_waitcnt lgkmcnt(0)
	v_add_f32_e32 v6, v6, v33
	v_mul_f32_e32 v6, 0x3b000000, v6
	v_fma_f32 v19, v19, v26, -v6
	v_fma_f32 v18, v18, v32, -v6
	v_mul_f32_e32 v19, v19, v19
	v_fma_f32 v20, v20, v28, -v6
	v_fmac_f32_e32 v19, v18, v18
	v_fma_f32 v21, v21, v30, -v6
	v_fmac_f32_e32 v19, v20, v20
	v_fma_f32 v7, v22, v7, -v6
	v_fmac_f32_e32 v19, v21, v21
	v_fma_f32 v22, v23, v27, -v6
	v_fmac_f32_e32 v19, v7, v7
	v_fma_f32 v23, v24, v29, -v6
	v_fmac_f32_e32 v19, v22, v22
	v_fmac_f32_e32 v19, v23, v23
	v_fma_f32 v7, v25, v31, -v6
	v_fmac_f32_e32 v19, v7, v7
	ds_bpermute_b32 v7, v9, v19
	s_waitcnt lgkmcnt(0)
	v_add_f32_e32 v7, v19, v7
	ds_bpermute_b32 v18, v10, v7
	s_waitcnt lgkmcnt(0)
	v_add_f32_e32 v7, v7, v18
	ds_bpermute_b32 v18, v11, v7
	s_waitcnt lgkmcnt(0)
	v_add_f32_e32 v7, v7, v18
	ds_bpermute_b32 v18, v12, v7
	s_waitcnt lgkmcnt(0)
	v_add_f32_e32 v7, v7, v18
	ds_bpermute_b32 v18, v13, v7
	s_waitcnt lgkmcnt(0)
	v_add_f32_e32 v7, v7, v18
	ds_bpermute_b32 v18, v16, v7
	s_and_saveexec_b64 s[56:57], s[42:43]
	s_cbranch_execz .LBB0_754
	s_waitcnt lgkmcnt(0)
	v_add_f32_e32 v7, v7, v18
	v_fmamk_f32 v7, v7, 0x3b000000, v194
	v_mul_f32_e32 v18, 0x4b800000, v7
	v_cmp_gt_f32_e32 vcc, s95, v7
	s_nop 1
	v_cndmask_b32_e32 v7, v7, v18, vcc
	v_rsq_f32_e32 v7, v7
	s_nop 0
	v_mul_f32_e32 v18, 0x45800000, v7
	v_cndmask_b32_e32 v7, v7, v18, vcc
	ds_write_b64 v17, v[6:7]
; DI float gelu_t(float x) { return x * sigm(1.5957691216057308f * (x + 0.044715f * x * x * x)); }
; DI void prep_a_prompt(LAS unsigned char* lds, const Params& P, int l, int unit) {
;     ...
; #pragma unroll 8
;     for (int i = 0; i < 16; ++i) { const int t = wave * 16 + i; const float* p = P32 + (size_t)(row0 + t) * LDP + C_AV + lane * 8;
;         const f32x4 a = *(const f32x4*)p, bq = *(const f32x4*)(p + 4); float x[8];
; #pragma unroll
;         for (int e = 0; e < 4; ++e) { x[e] = gelu_t(a[e]); x[4 + e] = gelu_t(bq[e]); }
;         float s = 0.f;
; #pragma unroll
;         for (int e = 0; e < 8; ++e) s += x[e];
;         const float mean = wsum(s) * (1.f / 512.f); float d = 0.f;
; #pragma unroll
;         for (int e = 0; e < 8; ++e) d += (x[e] - mean) * (x[e] - mean);
;         const float var = wsum(d) * (1.f / 512.f);
;         if (lane == 0) { st[t * 2] = mean; st[t * 2 + 1] = rsqrtf(var + 1e-6f); } }
.LBB0_754:
	s_or_b64 exec, exec, s[56:57]
	s_waitcnt lgkmcnt(0)
	v_add_co_u32_e32 v18, vcc, 0x7000, v4
	s_mov_b64 s[6:7], 0x7000
	s_nop 0
	v_addc_co_u32_e32 v19, vcc, 0, v5, vcc
	v_lshl_add_u64 v[6:7], v[4:5], 0, s[6:7]
	s_nop 0
	s_waitcnt vmcnt(13)
	v_mov_b32_e32 v18, v64
	v_mov_b32_e32 v19, v65
	v_mov_b32_e32 v20, v66
	v_mov_b32_e32 v21, v67
	v_mul_f32_e32 v6, 0x3d372713, v18
	v_mul_f32_e32 v26, 0x3d372713, v19
	v_mul_f32_e32 v6, v18, v6
	v_mul_f32_e32 v28, 0x3d372713, v20
	v_mul_f32_e32 v26, v19, v26
	v_fma_f32 v6, v18, v6, v18
	v_mul_f32_e32 v30, 0x3d372713, v21
	v_mul_f32_e32 v28, v20, v28
	v_fma_f32 v26, v19, v26, v19
	v_mul_f32_e32 v6, 0x3fcc422a, v6
	s_waitcnt vmcnt(12)
	v_mov_b32_e32 v22, v68
	v_mov_b32_e32 v23, v69
	v_mov_b32_e32 v24, v70
	v_mov_b32_e32 v25, v71
	v_mul_f32_e32 v7, 0x3d372713, v22
	v_mul_f32_e32 v30, v21, v30
	v_fma_f32 v28, v20, v28, v20
	v_mul_f32_e32 v26, 0x3fcc422a, v26
	v_mul_f32_e32 v6, 0xbfb8aa3b, v6
	v_mul_f32_e32 v27, 0x3d372713, v23
	v_mul_f32_e32 v7, v22, v7
	v_fma_f32 v30, v21, v30, v21
	v_mul_f32_e32 v28, 0x3fcc422a, v28
	v_mul_f32_e32 v26, 0xbfb8aa3b, v26
	v_exp_f32_e32 v6, v6
	v_mul_f32_e32 v29, 0x3d372713, v24
	v_mul_f32_e32 v27, v23, v27
	v_fma_f32 v7, v22, v7, v22
	v_mul_f32_e32 v30, 0x3fcc422a, v30
	v_mul_f32_e32 v28, 0xbfb8aa3b, v28
	v_exp_f32_e32 v26, v26
	v_mul_f32_e32 v31, 0x3d372713, v25
	v_mul_f32_e32 v29, v24, v29
	v_fma_f32 v27, v23, v27, v23
	v_mul_f32_e32 v7, 0x3fcc422a, v7
	v_mul_f32_e32 v30, 0xbfb8aa3b, v30
	v_exp_f32_e32 v28, v28
	v_mul_f32_e32 v31, v25, v31
	v_fma_f32 v29, v24, v29, v24
	v_mul_f32_e32 v27, 0x3fcc422a, v27
	v_mul_f32_e32 v7, 0xbfb8aa3b, v7
	v_exp_f32_e32 v30, v30
	v_fma_f32 v31, v25, v31, v25
	v_mul_f32_e32 v29, 0x3fcc422a, v29
	v_mul_f32_e32 v27, 0xbfb8aa3b, v27
	v_exp_f32_e32 v7, v7
	v_add_f32_e32 v6, 1.0, v6
	v_mul_f32_e32 v31, 0x3fcc422a, v31
	v_mul_f32_e32 v29, 0xbfb8aa3b, v29
	v_exp_f32_e32 v27, v27
	v_add_f32_e32 v26, 1.0, v26
	v_rcp_f32_e32 v32, v6
	v_mul_f32_e32 v31, 0xbfb8aa3b, v31
	v_exp_f32_e32 v29, v29
	v_add_f32_e32 v28, 1.0, v28
	v_rcp_f32_e32 v26, v26
	v_exp_f32_e32 v31, v31
	v_add_f32_e32 v30, 1.0, v30
	v_rcp_f32_e32 v28, v28
	v_add_f32_e32 v7, 1.0, v7
	v_rcp_f32_e32 v30, v30
	v_add_f32_e32 v27, 1.0, v27
	v_rcp_f32_e32 v7, v7
	v_fma_f32 v6, v18, v32, 0
	v_add_f32_e32 v29, 1.0, v29
	v_rcp_f32_e32 v27, v27
	v_fmac_f32_e32 v6, v19, v26
	v_add_f32_e32 v31, 1.0, v31
	v_rcp_f32_e32 v29, v29
	v_fmac_f32_e32 v6, v20, v28
	v_rcp_f32_e32 v31, v31
	v_fmac_f32_e32 v6, v21, v30
	v_fmac_f32_e32 v6, v22, v7
	v_fmac_f32_e32 v6, v23, v27
	v_fmac_f32_e32 v6, v24, v29
	v_fmac_f32_e32 v6, v25, v31
	ds_bpermute_b32 v33, v9, v6
	s_waitcnt lgkmcnt(0)
	v_add_f32_e32 v6, v6, v33
	ds_bpermute_b32 v33, v10, v6
	s_waitcnt lgkmcnt(0)
	v_add_f32_e32 v6, v6, v33
	ds_bpermute_b32 v33, v11, v6
	s_waitcnt lgkmcnt(0)
	v_add_f32_e32 v6, v6, v33
	ds_bpermute_b32 v33, v12, v6
	s_waitcnt lgkmcnt(0)
	v_add_f32_e32 v6, v6, v33
	ds_bpermute_b32 v33, v13, v6
	s_waitcnt lgkmcnt(0)
	v_add_f32_e32 v6, v6, v33
	ds_bpermute_b32 v33, v16, v6
	s_waitcnt lgkmcnt(0)
	v_add_f32_e32 v6, v6, v33
	v_mul_f32_e32 v6, 0x3b000000, v6
	v_fma_f32 v19, v19, v26, -v6
	v_fma_f32 v18, v18, v32, -v6
	v_mul_f32_e32 v19, v19, v19
	v_fma_f32 v20, v20, v28, -v6
	v_fmac_f32_e32 v19, v18, v18
	v_fma_f32 v21, v21, v30, -v6
	v_fmac_f32_e32 v19, v20, v20
	v_fma_f32 v7, v22, v7, -v6
	v_fmac_f32_e32 v19, v21, v21
	v_fma_f32 v22, v23, v27, -v6
	v_fmac_f32_e32 v19, v7, v7
	v_fma_f32 v23, v24, v29, -v6
	v_fmac_f32_e32 v19, v22, v22
	v_fmac_f32_e32 v19, v23, v23
	v_fma_f32 v7, v25, v31, -v6
	v_fmac_f32_e32 v19, v7, v7
	ds_bpermute_b32 v7, v9, v19
	s_waitcnt lgkmcnt(0)
	v_add_f32_e32 v7, v19, v7
	ds_bpermute_b32 v18, v10, v7
	s_waitcnt lgkmcnt(0)
	v_add_f32_e32 v7, v7, v18
	ds_bpermute_b32 v18, v11, v7
	s_waitcnt lgkmcnt(0)
	v_add_f32_e32 v7, v7, v18
	ds_bpermute_b32 v18, v12, v7
	s_waitcnt lgkmcnt(0)
	v_add_f32_e32 v7, v7, v18
	ds_bpermute_b32 v18, v13, v7
	s_waitcnt lgkmcnt(0)
	v_add_f32_e32 v7, v7, v18
	ds_bpermute_b32 v18, v16, v7
	s_and_saveexec_b64 s[56:57], s[42:43]
	s_cbranch_execz .LBB0_756
	s_waitcnt lgkmcnt(0)
	v_add_f32_e32 v7, v7, v18
	v_fmamk_f32 v7, v7, 0x3b000000, v194
	v_mul_f32_e32 v18, 0x4b800000, v7
	v_cmp_gt_f32_e32 vcc, s95, v7
	s_nop 1
	v_cndmask_b32_e32 v7, v7, v18, vcc
	v_rsq_f32_e32 v7, v7
	s_nop 0
	v_mul_f32_e32 v18, 0x45800000, v7
	v_cndmask_b32_e32 v7, v7, v18, vcc
	ds_write_b64 v17, v[6:7] offset:8
; DI float gelu_t(float x) { return x * sigm(1.5957691216057308f * (x + 0.044715f * x * x * x)); }
; DI void prep_a_prompt(LAS unsigned char* lds, const Params& P, int l, int unit) {
;     ...
; #pragma unroll 8
;     for (int i = 0; i < 16; ++i) { const int t = wave * 16 + i; const float* p = P32 + (size_t)(row0 + t) * LDP + C_AV + lane * 8;
;         const f32x4 a = *(const f32x4*)p, bq = *(const f32x4*)(p + 4); float x[8];
; #pragma unroll
;         for (int e = 0; e < 4; ++e) { x[e] = gelu_t(a[e]); x[4 + e] = gelu_t(bq[e]); }
;         float s = 0.f;
; #pragma unroll
;         for (int e = 0; e < 8; ++e) s += x[e];
;         const float mean = wsum(s) * (1.f / 512.f); float d = 0.f;
; #pragma unroll
;         for (int e = 0; e < 8; ++e) d += (x[e] - mean) * (x[e] - mean);
;         const float var = wsum(d) * (1.f / 512.f);
;         if (lane == 0) { st[t * 2] = mean; st[t * 2 + 1] = rsqrtf(var + 1e-6f); } }
.LBB0_756:
	s_or_b64 exec, exec, s[56:57]
	s_waitcnt lgkmcnt(0)
	v_add_co_u32_e32 v18, vcc, 0xd000, v4
	s_mov_b64 s[6:7], 0xd800
	s_nop 0
	v_addc_co_u32_e32 v19, vcc, 0, v5, vcc
	v_lshl_add_u64 v[6:7], v[4:5], 0, s[6:7]
	s_nop 0
	s_waitcnt vmcnt(11)
	v_mov_b32_e32 v18, v72
	v_mov_b32_e32 v19, v73
	v_mov_b32_e32 v20, v74
	v_mov_b32_e32 v21, v75
	v_mul_f32_e32 v6, 0x3d372713, v18
	v_mul_f32_e32 v26, 0x3d372713, v19
	v_mul_f32_e32 v6, v18, v6
	v_mul_f32_e32 v28, 0x3d372713, v20
	v_mul_f32_e32 v26, v19, v26
	v_fma_f32 v6, v18, v6, v18
	v_mul_f32_e32 v30, 0x3d372713, v21
	v_mul_f32_e32 v28, v20, v28
	v_fma_f32 v26, v19, v26, v19
	v_mul_f32_e32 v6, 0x3fcc422a, v6
	s_waitcnt vmcnt(10)
	v_mov_b32_e32 v22, v76
	v_mov_b32_e32 v23, v77
	v_mov_b32_e32 v24, v78
	v_mov_b32_e32 v25, v79
	v_mul_f32_e32 v7, 0x3d372713, v22
	v_mul_f32_e32 v30, v21, v30
	v_fma_f32 v28, v20, v28, v20
	v_mul_f32_e32 v26, 0x3fcc422a, v26
	v_mul_f32_e32 v6, 0xbfb8aa3b, v6
	v_mul_f32_e32 v27, 0x3d372713, v23
	v_mul_f32_e32 v7, v22, v7
	v_fma_f32 v30, v21, v30, v21
	v_mul_f32_e32 v28, 0x3fcc422a, v28
	v_mul_f32_e32 v26, 0xbfb8aa3b, v26
	v_exp_f32_e32 v6, v6
	v_mul_f32_e32 v29, 0x3d372713, v24
	v_mul_f32_e32 v27, v23, v27
	v_fma_f32 v7, v22, v7, v22
	v_mul_f32_e32 v30, 0x3fcc422a, v30
	v_mul_f32_e32 v28, 0xbfb8aa3b, v28
	v_exp_f32_e32 v26, v26
	v_mul_f32_e32 v31, 0x3d372713, v25
	v_mul_f32_e32 v29, v24, v29
	v_fma_f32 v27, v23, v27, v23
	v_mul_f32_e32 v7, 0x3fcc422a, v7
	v_mul_f32_e32 v30, 0xbfb8aa3b, v30
	v_exp_f32_e32 v28, v28
	v_mul_f32_e32 v31, v25, v31
	v_fma_f32 v29, v24, v29, v24
	v_mul_f32_e32 v27, 0x3fcc422a, v27
	v_mul_f32_e32 v7, 0xbfb8aa3b, v7
	v_exp_f32_e32 v30, v30
	v_fma_f32 v31, v25, v31, v25
	v_mul_f32_e32 v29, 0x3fcc422a, v29
	v_mul_f32_e32 v27, 0xbfb8aa3b, v27
	v_exp_f32_e32 v7, v7
	v_add_f32_e32 v6, 1.0, v6
	v_mul_f32_e32 v31, 0x3fcc422a, v31
	v_mul_f32_e32 v29, 0xbfb8aa3b, v29
	v_exp_f32_e32 v27, v27
	v_add_f32_e32 v26, 1.0, v26
	v_rcp_f32_e32 v32, v6
	v_mul_f32_e32 v31, 0xbfb8aa3b, v31
	v_exp_f32_e32 v29, v29
	v_add_f32_e32 v28, 1.0, v28
	v_rcp_f32_e32 v26, v26
	v_exp_f32_e32 v31, v31
	v_add_f32_e32 v30, 1.0, v30
	v_rcp_f32_e32 v28, v28
	v_add_f32_e32 v7, 1.0, v7
	v_rcp_f32_e32 v30, v30
	v_add_f32_e32 v27, 1.0, v27
	v_rcp_f32_e32 v7, v7
	v_fma_f32 v6, v18, v32, 0
	v_add_f32_e32 v29, 1.0, v29
	v_rcp_f32_e32 v27, v27
	v_fmac_f32_e32 v6, v19, v26
	v_add_f32_e32 v31, 1.0, v31
	v_rcp_f32_e32 v29, v29
	v_fmac_f32_e32 v6, v20, v28
	v_rcp_f32_e32 v31, v31
	v_fmac_f32_e32 v6, v21, v30
	v_fmac_f32_e32 v6, v22, v7
	v_fmac_f32_e32 v6, v23, v27
	v_fmac_f32_e32 v6, v24, v29
	v_fmac_f32_e32 v6, v25, v31
	ds_bpermute_b32 v33, v9, v6
	s_waitcnt lgkmcnt(0)
	v_add_f32_e32 v6, v6, v33
	ds_bpermute_b32 v33, v10, v6
	s_waitcnt lgkmcnt(0)
	v_add_f32_e32 v6, v6, v33
	ds_bpermute_b32 v33, v11, v6
	s_waitcnt lgkmcnt(0)
	v_add_f32_e32 v6, v6, v33
	ds_bpermute_b32 v33, v12, v6
	s_waitcnt lgkmcnt(0)
	v_add_f32_e32 v6, v6, v33
	ds_bpermute_b32 v33, v13, v6
	s_waitcnt lgkmcnt(0)
	v_add_f32_e32 v6, v6, v33
	ds_bpermute_b32 v33, v16, v6
	s_waitcnt lgkmcnt(0)
	v_add_f32_e32 v6, v6, v33
	v_mul_f32_e32 v6, 0x3b000000, v6
	v_fma_f32 v19, v19, v26, -v6
	v_fma_f32 v18, v18, v32, -v6
	v_mul_f32_e32 v19, v19, v19
	v_fma_f32 v20, v20, v28, -v6
	v_fmac_f32_e32 v19, v18, v18
	v_fma_f32 v21, v21, v30, -v6
	v_fmac_f32_e32 v19, v20, v20
	v_fma_f32 v7, v22, v7, -v6
	v_fmac_f32_e32 v19, v21, v21
	v_fma_f32 v22, v23, v27, -v6
	v_fmac_f32_e32 v19, v7, v7
	v_fma_f32 v23, v24, v29, -v6
	v_fmac_f32_e32 v19, v22, v22
	v_fmac_f32_e32 v19, v23, v23
	v_fma_f32 v7, v25, v31, -v6
	v_fmac_f32_e32 v19, v7, v7
	ds_bpermute_b32 v7, v9, v19
	s_waitcnt lgkmcnt(0)
	v_add_f32_e32 v7, v19, v7
	ds_bpermute_b32 v18, v10, v7
	s_waitcnt lgkmcnt(0)
	v_add_f32_e32 v7, v7, v18
	ds_bpermute_b32 v18, v11, v7
	s_waitcnt lgkmcnt(0)
	v_add_f32_e32 v7, v7, v18
	ds_bpermute_b32 v18, v12, v7
	s_waitcnt lgkmcnt(0)
	v_add_f32_e32 v7, v7, v18
	ds_bpermute_b32 v18, v13, v7
	s_waitcnt lgkmcnt(0)
	v_add_f32_e32 v7, v7, v18
	ds_bpermute_b32 v18, v16, v7
	s_and_saveexec_b64 s[56:57], s[42:43]
	s_cbranch_execz .LBB0_758
	s_waitcnt lgkmcnt(0)
	v_add_f32_e32 v7, v7, v18
	v_fmamk_f32 v7, v7, 0x3b000000, v194
	v_mul_f32_e32 v18, 0x4b800000, v7
	v_cmp_gt_f32_e32 vcc, s95, v7
	s_nop 1
	v_cndmask_b32_e32 v7, v7, v18, vcc
	v_rsq_f32_e32 v7, v7
	s_nop 0
	v_mul_f32_e32 v18, 0x45800000, v7
	v_cndmask_b32_e32 v7, v7, v18, vcc
	ds_write_b64 v17, v[6:7] offset:16
; DI float gelu_t(float x) { return x * sigm(1.5957691216057308f * (x + 0.044715f * x * x * x)); }
; DI void prep_a_prompt(LAS unsigned char* lds, const Params& P, int l, int unit) {
;     ...
; #pragma unroll 8
;     for (int i = 0; i < 16; ++i) { const int t = wave * 16 + i; const float* p = P32 + (size_t)(row0 + t) * LDP + C_AV + lane * 8;
;         const f32x4 a = *(const f32x4*)p, bq = *(const f32x4*)(p + 4); float x[8];
; #pragma unroll
;         for (int e = 0; e < 4; ++e) { x[e] = gelu_t(a[e]); x[4 + e] = gelu_t(bq[e]); }
;         float s = 0.f;
; #pragma unroll
;         for (int e = 0; e < 8; ++e) s += x[e];
;         const float mean = wsum(s) * (1.f / 512.f); float d = 0.f;
; #pragma unroll
;         for (int e = 0; e < 8; ++e) d += (x[e] - mean) * (x[e] - mean);
;         const float var = wsum(d) * (1.f / 512.f);
;         if (lane == 0) { st[t * 2] = mean; st[t * 2 + 1] = rsqrtf(var + 1e-6f); } }
.LBB0_758:
	s_or_b64 exec, exec, s[56:57]
	s_waitcnt lgkmcnt(0)
	v_add_co_u32_e32 v18, vcc, 0x14000, v4
	s_mov_b64 s[6:7], 0x14000
	s_nop 0
	v_addc_co_u32_e32 v19, vcc, 0, v5, vcc
	v_lshl_add_u64 v[6:7], v[4:5], 0, s[6:7]
	s_nop 0
	s_waitcnt vmcnt(9)
	v_mov_b32_e32 v18, v80
	v_mov_b32_e32 v19, v81
	v_mov_b32_e32 v20, v82
	v_mov_b32_e32 v21, v83
	v_mul_f32_e32 v6, 0x3d372713, v18
	v_mul_f32_e32 v26, 0x3d372713, v19
	v_mul_f32_e32 v6, v18, v6
	v_mul_f32_e32 v28, 0x3d372713, v20
	v_mul_f32_e32 v26, v19, v26
	v_fma_f32 v6, v18, v6, v18
	v_mul_f32_e32 v30, 0x3d372713, v21
	v_mul_f32_e32 v28, v20, v28
	v_fma_f32 v26, v19, v26, v19
	v_mul_f32_e32 v6, 0x3fcc422a, v6
	s_waitcnt vmcnt(8)
	v_mov_b32_e32 v22, v84
	v_mov_b32_e32 v23, v85
	v_mov_b32_e32 v24, v86
	v_mov_b32_e32 v25, v87
	v_mul_f32_e32 v7, 0x3d372713, v22
	v_mul_f32_e32 v30, v21, v30
	v_fma_f32 v28, v20, v28, v20
	v_mul_f32_e32 v26, 0x3fcc422a, v26
	v_mul_f32_e32 v6, 0xbfb8aa3b, v6
	v_mul_f32_e32 v27, 0x3d372713, v23
	v_mul_f32_e32 v7, v22, v7
	v_fma_f32 v30, v21, v30, v21
	v_mul_f32_e32 v28, 0x3fcc422a, v28
	v_mul_f32_e32 v26, 0xbfb8aa3b, v26
	v_exp_f32_e32 v6, v6
	v_mul_f32_e32 v29, 0x3d372713, v24
	v_mul_f32_e32 v27, v23, v27
	v_fma_f32 v7, v22, v7, v22
	v_mul_f32_e32 v30, 0x3fcc422a, v30
	v_mul_f32_e32 v28, 0xbfb8aa3b, v28
	v_exp_f32_e32 v26, v26
	v_mul_f32_e32 v31, 0x3d372713, v25
	v_mul_f32_e32 v29, v24, v29
	v_fma_f32 v27, v23, v27, v23
	v_mul_f32_e32 v7, 0x3fcc422a, v7
	v_mul_f32_e32 v30, 0xbfb8aa3b, v30
	v_exp_f32_e32 v28, v28
	v_mul_f32_e32 v31, v25, v31
	v_fma_f32 v29, v24, v29, v24
	v_mul_f32_e32 v27, 0x3fcc422a, v27
	v_mul_f32_e32 v7, 0xbfb8aa3b, v7
	v_exp_f32_e32 v30, v30
	v_fma_f32 v31, v25, v31, v25
	v_mul_f32_e32 v29, 0x3fcc422a, v29
	v_mul_f32_e32 v27, 0xbfb8aa3b, v27
	v_exp_f32_e32 v7, v7
	v_add_f32_e32 v6, 1.0, v6
	v_mul_f32_e32 v31, 0x3fcc422a, v31
	v_mul_f32_e32 v29, 0xbfb8aa3b, v29
	v_exp_f32_e32 v27, v27
	v_add_f32_e32 v26, 1.0, v26
	v_rcp_f32_e32 v32, v6
	v_mul_f32_e32 v31, 0xbfb8aa3b, v31
	v_exp_f32_e32 v29, v29
	v_add_f32_e32 v28, 1.0, v28
	v_rcp_f32_e32 v26, v26
	v_exp_f32_e32 v31, v31
	v_add_f32_e32 v30, 1.0, v30
	v_rcp_f32_e32 v28, v28
	v_add_f32_e32 v7, 1.0, v7
	v_rcp_f32_e32 v30, v30
	v_add_f32_e32 v27, 1.0, v27
	v_rcp_f32_e32 v7, v7
	v_fma_f32 v6, v18, v32, 0
	v_add_f32_e32 v29, 1.0, v29
	v_rcp_f32_e32 v27, v27
	v_fmac_f32_e32 v6, v19, v26
	v_add_f32_e32 v31, 1.0, v31
	v_rcp_f32_e32 v29, v29
	v_fmac_f32_e32 v6, v20, v28
	v_rcp_f32_e32 v31, v31
	v_fmac_f32_e32 v6, v21, v30
	v_fmac_f32_e32 v6, v22, v7
	v_fmac_f32_e32 v6, v23, v27
	v_fmac_f32_e32 v6, v24, v29
	v_fmac_f32_e32 v6, v25, v31
	ds_bpermute_b32 v33, v9, v6
	s_waitcnt lgkmcnt(0)
	v_add_f32_e32 v6, v6, v33
	ds_bpermute_b32 v33, v10, v6
	s_waitcnt lgkmcnt(0)
	v_add_f32_e32 v6, v6, v33
	ds_bpermute_b32 v33, v11, v6
	s_waitcnt lgkmcnt(0)
	v_add_f32_e32 v6, v6, v33
	ds_bpermute_b32 v33, v12, v6
	s_waitcnt lgkmcnt(0)
	v_add_f32_e32 v6, v6, v33
	ds_bpermute_b32 v33, v13, v6
	s_waitcnt lgkmcnt(0)
	v_add_f32_e32 v6, v6, v33
	ds_bpermute_b32 v33, v16, v6
	s_waitcnt lgkmcnt(0)
	v_add_f32_e32 v6, v6, v33
	v_mul_f32_e32 v6, 0x3b000000, v6
	v_fma_f32 v19, v19, v26, -v6
	v_fma_f32 v18, v18, v32, -v6
	v_mul_f32_e32 v19, v19, v19
	v_fma_f32 v20, v20, v28, -v6
	v_fmac_f32_e32 v19, v18, v18
	v_fma_f32 v21, v21, v30, -v6
	v_fmac_f32_e32 v19, v20, v20
	v_fma_f32 v7, v22, v7, -v6
	v_fmac_f32_e32 v19, v21, v21
	v_fma_f32 v22, v23, v27, -v6
	v_fmac_f32_e32 v19, v7, v7
	v_fma_f32 v23, v24, v29, -v6
	v_fmac_f32_e32 v19, v22, v22
	v_fmac_f32_e32 v19, v23, v23
	v_fma_f32 v7, v25, v31, -v6
	v_fmac_f32_e32 v19, v7, v7
	ds_bpermute_b32 v7, v9, v19
	s_waitcnt lgkmcnt(0)
	v_add_f32_e32 v7, v19, v7
	ds_bpermute_b32 v18, v10, v7
	s_waitcnt lgkmcnt(0)
	v_add_f32_e32 v7, v7, v18
	ds_bpermute_b32 v18, v11, v7
	s_waitcnt lgkmcnt(0)
	v_add_f32_e32 v7, v7, v18
	ds_bpermute_b32 v18, v12, v7
	s_waitcnt lgkmcnt(0)
	v_add_f32_e32 v7, v7, v18
	ds_bpermute_b32 v18, v13, v7
	s_waitcnt lgkmcnt(0)
	v_add_f32_e32 v7, v7, v18
	ds_bpermute_b32 v18, v16, v7
	s_and_saveexec_b64 s[56:57], s[42:43]
	s_cbranch_execz .LBB0_760
	s_waitcnt lgkmcnt(0)
	v_add_f32_e32 v7, v7, v18
	v_fmamk_f32 v7, v7, 0x3b000000, v194
	v_mul_f32_e32 v18, 0x4b800000, v7
	v_cmp_gt_f32_e32 vcc, s95, v7
	s_nop 1
	v_cndmask_b32_e32 v7, v7, v18, vcc
	v_rsq_f32_e32 v7, v7
	s_nop 0
	v_mul_f32_e32 v18, 0x45800000, v7
	v_cndmask_b32_e32 v7, v7, v18, vcc
	ds_write_b64 v17, v[6:7] offset:24
; DI float gelu_t(float x) { return x * sigm(1.5957691216057308f * (x + 0.044715f * x * x * x)); }
; DI void prep_a_prompt(LAS unsigned char* lds, const Params& P, int l, int unit) {
;     ...
; #pragma unroll 8
;     for (int i = 0; i < 16; ++i) { const int t = wave * 16 + i; const float* p = P32 + (size_t)(row0 + t) * LDP + C_AV + lane * 8;
;         const f32x4 a = *(const f32x4*)p, bq = *(const f32x4*)(p + 4); float x[8];
; #pragma unroll
;         for (int e = 0; e < 4; ++e) { x[e] = gelu_t(a[e]); x[4 + e] = gelu_t(bq[e]); }
;         float s = 0.f;
; #pragma unroll
;         for (int e = 0; e < 8; ++e) s += x[e];
;         const float mean = wsum(s) * (1.f / 512.f); float d = 0.f;
; #pragma unroll
;         for (int e = 0; e < 8; ++e) d += (x[e] - mean) * (x[e] - mean);
;         const float var = wsum(d) * (1.f / 512.f);
;         if (lane == 0) { st[t * 2] = mean; st[t * 2 + 1] = rsqrtf(var + 1e-6f); } }
.LBB0_760:
	s_or_b64 exec, exec, s[56:57]
	s_waitcnt lgkmcnt(0)
	v_add_co_u32_e32 v18, vcc, 0x1a000, v4
	s_mov_b64 s[6:7], 0x1a800
	s_nop 0
	v_addc_co_u32_e32 v19, vcc, 0, v5, vcc
	v_lshl_add_u64 v[6:7], v[4:5], 0, s[6:7]
	s_nop 0
	s_waitcnt vmcnt(7)
	v_mov_b32_e32 v18, v88
	v_mov_b32_e32 v19, v89
	v_mov_b32_e32 v20, v90
	v_mov_b32_e32 v21, v91
	v_mul_f32_e32 v6, 0x3d372713, v18
	v_mul_f32_e32 v26, 0x3d372713, v19
	v_mul_f32_e32 v6, v18, v6
	v_mul_f32_e32 v28, 0x3d372713, v20
	v_mul_f32_e32 v26, v19, v26
	v_fma_f32 v6, v18, v6, v18
	v_mul_f32_e32 v30, 0x3d372713, v21
	v_mul_f32_e32 v28, v20, v28
	v_fma_f32 v26, v19, v26, v19
	v_mul_f32_e32 v6, 0x3fcc422a, v6
	s_waitcnt vmcnt(6)
	v_mov_b32_e32 v22, v92
	v_mov_b32_e32 v23, v93
	v_mov_b32_e32 v24, v94
	v_mov_b32_e32 v25, v95
	v_mul_f32_e32 v7, 0x3d372713, v22
	v_mul_f32_e32 v30, v21, v30
	v_fma_f32 v28, v20, v28, v20
	v_mul_f32_e32 v26, 0x3fcc422a, v26
	v_mul_f32_e32 v6, 0xbfb8aa3b, v6
	v_mul_f32_e32 v27, 0x3d372713, v23
	v_mul_f32_e32 v7, v22, v7
	v_fma_f32 v30, v21, v30, v21
	v_mul_f32_e32 v28, 0x3fcc422a, v28
	v_mul_f32_e32 v26, 0xbfb8aa3b, v26
	v_exp_f32_e32 v6, v6
	v_mul_f32_e32 v29, 0x3d372713, v24
	v_mul_f32_e32 v27, v23, v27
	v_fma_f32 v7, v22, v7, v22
	v_mul_f32_e32 v30, 0x3fcc422a, v30
	v_mul_f32_e32 v28, 0xbfb8aa3b, v28
	v_exp_f32_e32 v26, v26
	v_mul_f32_e32 v31, 0x3d372713, v25
	v_mul_f32_e32 v29, v24, v29
	v_fma_f32 v27, v23, v27, v23
	v_mul_f32_e32 v7, 0x3fcc422a, v7
	v_mul_f32_e32 v30, 0xbfb8aa3b, v30
	v_exp_f32_e32 v28, v28
	v_mul_f32_e32 v31, v25, v31
	v_fma_f32 v29, v24, v29, v24
	v_mul_f32_e32 v27, 0x3fcc422a, v27
	v_mul_f32_e32 v7, 0xbfb8aa3b, v7
	v_exp_f32_e32 v30, v30
	v_fma_f32 v31, v25, v31, v25
	v_mul_f32_e32 v29, 0x3fcc422a, v29
	v_mul_f32_e32 v27, 0xbfb8aa3b, v27
	v_exp_f32_e32 v7, v7
	v_add_f32_e32 v6, 1.0, v6
	v_mul_f32_e32 v31, 0x3fcc422a, v31
	v_mul_f32_e32 v29, 0xbfb8aa3b, v29
	v_exp_f32_e32 v27, v27
	v_add_f32_e32 v26, 1.0, v26
	v_rcp_f32_e32 v32, v6
	v_mul_f32_e32 v31, 0xbfb8aa3b, v31
	v_exp_f32_e32 v29, v29
	v_add_f32_e32 v28, 1.0, v28
	v_rcp_f32_e32 v26, v26
	v_exp_f32_e32 v31, v31
	v_add_f32_e32 v30, 1.0, v30
	v_rcp_f32_e32 v28, v28
	v_add_f32_e32 v7, 1.0, v7
	v_rcp_f32_e32 v30, v30
	v_add_f32_e32 v27, 1.0, v27
	v_rcp_f32_e32 v7, v7
	v_fma_f32 v6, v18, v32, 0
	v_add_f32_e32 v29, 1.0, v29
	v_rcp_f32_e32 v27, v27
	v_fmac_f32_e32 v6, v19, v26
	v_add_f32_e32 v31, 1.0, v31
	v_rcp_f32_e32 v29, v29
	v_fmac_f32_e32 v6, v20, v28
	v_rcp_f32_e32 v31, v31
	v_fmac_f32_e32 v6, v21, v30
	v_fmac_f32_e32 v6, v22, v7
	v_fmac_f32_e32 v6, v23, v27
	v_fmac_f32_e32 v6, v24, v29
	v_fmac_f32_e32 v6, v25, v31
	ds_bpermute_b32 v33, v9, v6
	s_waitcnt lgkmcnt(0)
	v_add_f32_e32 v6, v6, v33
	ds_bpermute_b32 v33, v10, v6
	s_waitcnt lgkmcnt(0)
	v_add_f32_e32 v6, v6, v33
	ds_bpermute_b32 v33, v11, v6
	s_waitcnt lgkmcnt(0)
	v_add_f32_e32 v6, v6, v33
	ds_bpermute_b32 v33, v12, v6
	s_waitcnt lgkmcnt(0)
	v_add_f32_e32 v6, v6, v33
	ds_bpermute_b32 v33, v13, v6
	s_waitcnt lgkmcnt(0)
	v_add_f32_e32 v6, v6, v33
	ds_bpermute_b32 v33, v16, v6
	s_waitcnt lgkmcnt(0)
	v_add_f32_e32 v6, v6, v33
	v_mul_f32_e32 v6, 0x3b000000, v6
	v_fma_f32 v19, v19, v26, -v6
	v_fma_f32 v18, v18, v32, -v6
	v_mul_f32_e32 v19, v19, v19
	v_fma_f32 v20, v20, v28, -v6
	v_fmac_f32_e32 v19, v18, v18
	v_fma_f32 v21, v21, v30, -v6
	v_fmac_f32_e32 v19, v20, v20
	v_fma_f32 v7, v22, v7, -v6
	v_fmac_f32_e32 v19, v21, v21
	v_fma_f32 v22, v23, v27, -v6
	v_fmac_f32_e32 v19, v7, v7
	v_fma_f32 v23, v24, v29, -v6
	v_fmac_f32_e32 v19, v22, v22
	v_fmac_f32_e32 v19, v23, v23
	v_fma_f32 v7, v25, v31, -v6
	v_fmac_f32_e32 v19, v7, v7
	ds_bpermute_b32 v7, v9, v19
	s_waitcnt lgkmcnt(0)
	v_add_f32_e32 v7, v19, v7
	ds_bpermute_b32 v18, v10, v7
	s_waitcnt lgkmcnt(0)
	v_add_f32_e32 v7, v7, v18
	ds_bpermute_b32 v18, v11, v7
	s_waitcnt lgkmcnt(0)
	v_add_f32_e32 v7, v7, v18
	ds_bpermute_b32 v18, v12, v7
	s_waitcnt lgkmcnt(0)
	v_add_f32_e32 v7, v7, v18
	ds_bpermute_b32 v18, v13, v7
	s_waitcnt lgkmcnt(0)
	v_add_f32_e32 v7, v7, v18
	ds_bpermute_b32 v18, v16, v7
	s_and_saveexec_b64 s[56:57], s[42:43]
	s_cbranch_execz .LBB0_762
	s_waitcnt lgkmcnt(0)
	v_add_f32_e32 v7, v7, v18
	v_fmamk_f32 v7, v7, 0x3b000000, v194
	v_mul_f32_e32 v18, 0x4b800000, v7
	v_cmp_gt_f32_e32 vcc, s95, v7
	s_nop 1
	v_cndmask_b32_e32 v7, v7, v18, vcc
	v_rsq_f32_e32 v7, v7
	s_nop 0
	v_mul_f32_e32 v18, 0x45800000, v7
	v_cndmask_b32_e32 v7, v7, v18, vcc
	ds_write_b64 v17, v[6:7] offset:32
; DI float gelu_t(float x) { return x * sigm(1.5957691216057308f * (x + 0.044715f * x * x * x)); }
; DI void prep_a_prompt(LAS unsigned char* lds, const Params& P, int l, int unit) {
;     ...
; #pragma unroll 8
;     for (int i = 0; i < 16; ++i) { const int t = wave * 16 + i; const float* p = P32 + (size_t)(row0 + t) * LDP + C_AV + lane * 8;
;         const f32x4 a = *(const f32x4*)p, bq = *(const f32x4*)(p + 4); float x[8];
; #pragma unroll
;         for (int e = 0; e < 4; ++e) { x[e] = gelu_t(a[e]); x[4 + e] = gelu_t(bq[e]); }
;         float s = 0.f;
; #pragma unroll
;         for (int e = 0; e < 8; ++e) s += x[e];
;         const float mean = wsum(s) * (1.f / 512.f); float d = 0.f;
; #pragma unroll
;         for (int e = 0; e < 8; ++e) d += (x[e] - mean) * (x[e] - mean);
;         const float var = wsum(d) * (1.f / 512.f);
;         if (lane == 0) { st[t * 2] = mean; st[t * 2 + 1] = rsqrtf(var + 1e-6f); } }
.LBB0_762:
	s_or_b64 exec, exec, s[56:57]
	s_waitcnt lgkmcnt(0)
	v_add_co_u32_e32 v18, vcc, 0x21000, v4
	s_mov_b64 s[6:7], 0x21000
	s_nop 0
	v_addc_co_u32_e32 v19, vcc, 0, v5, vcc
	v_lshl_add_u64 v[6:7], v[4:5], 0, s[6:7]
	s_nop 0
	s_waitcnt vmcnt(5)
	v_mov_b32_e32 v18, v96
	v_mov_b32_e32 v19, v97
	v_mov_b32_e32 v20, v98
	v_mov_b32_e32 v21, v99
	v_mul_f32_e32 v6, 0x3d372713, v18
	v_mul_f32_e32 v26, 0x3d372713, v19
	v_mul_f32_e32 v6, v18, v6
	v_mul_f32_e32 v28, 0x3d372713, v20
	v_mul_f32_e32 v26, v19, v26
	v_fma_f32 v6, v18, v6, v18
	v_mul_f32_e32 v30, 0x3d372713, v21
	v_mul_f32_e32 v28, v20, v28
	v_fma_f32 v26, v19, v26, v19
	v_mul_f32_e32 v6, 0x3fcc422a, v6
	s_waitcnt vmcnt(4)
	v_mov_b32_e32 v22, v100
	v_mov_b32_e32 v23, v101
	v_mov_b32_e32 v24, v102
	v_mov_b32_e32 v25, v103
	v_mul_f32_e32 v7, 0x3d372713, v22
	v_mul_f32_e32 v30, v21, v30
	v_fma_f32 v28, v20, v28, v20
	v_mul_f32_e32 v26, 0x3fcc422a, v26
	v_mul_f32_e32 v6, 0xbfb8aa3b, v6
	v_mul_f32_e32 v27, 0x3d372713, v23
	v_mul_f32_e32 v7, v22, v7
	v_fma_f32 v30, v21, v30, v21
	v_mul_f32_e32 v28, 0x3fcc422a, v28
	v_mul_f32_e32 v26, 0xbfb8aa3b, v26
	v_exp_f32_e32 v6, v6
	v_mul_f32_e32 v29, 0x3d372713, v24
	v_mul_f32_e32 v27, v23, v27
	v_fma_f32 v7, v22, v7, v22
	v_mul_f32_e32 v30, 0x3fcc422a, v30
	v_mul_f32_e32 v28, 0xbfb8aa3b, v28
	v_exp_f32_e32 v26, v26
	v_mul_f32_e32 v31, 0x3d372713, v25
	v_mul_f32_e32 v29, v24, v29
	v_fma_f32 v27, v23, v27, v23
	v_mul_f32_e32 v7, 0x3fcc422a, v7
	v_mul_f32_e32 v30, 0xbfb8aa3b, v30
	v_exp_f32_e32 v28, v28
	v_mul_f32_e32 v31, v25, v31
	v_fma_f32 v29, v24, v29, v24
	v_mul_f32_e32 v27, 0x3fcc422a, v27
	v_mul_f32_e32 v7, 0xbfb8aa3b, v7
	v_exp_f32_e32 v30, v30
	v_fma_f32 v31, v25, v31, v25
	v_mul_f32_e32 v29, 0x3fcc422a, v29
	v_mul_f32_e32 v27, 0xbfb8aa3b, v27
	v_exp_f32_e32 v7, v7
	v_add_f32_e32 v6, 1.0, v6
	v_mul_f32_e32 v31, 0x3fcc422a, v31
	v_mul_f32_e32 v29, 0xbfb8aa3b, v29
	v_exp_f32_e32 v27, v27
	v_add_f32_e32 v26, 1.0, v26
	v_rcp_f32_e32 v32, v6
	v_mul_f32_e32 v31, 0xbfb8aa3b, v31
	v_exp_f32_e32 v29, v29
	v_add_f32_e32 v28, 1.0, v28
	v_rcp_f32_e32 v26, v26
	v_exp_f32_e32 v31, v31
	v_add_f32_e32 v30, 1.0, v30
	v_rcp_f32_e32 v28, v28
	v_add_f32_e32 v7, 1.0, v7
	v_rcp_f32_e32 v30, v30
	v_add_f32_e32 v27, 1.0, v27
	v_rcp_f32_e32 v7, v7
	v_fma_f32 v6, v18, v32, 0
	v_add_f32_e32 v29, 1.0, v29
	v_rcp_f32_e32 v27, v27
	v_fmac_f32_e32 v6, v19, v26
	v_add_f32_e32 v31, 1.0, v31
	v_rcp_f32_e32 v29, v29
	v_fmac_f32_e32 v6, v20, v28
	v_rcp_f32_e32 v31, v31
	v_fmac_f32_e32 v6, v21, v30
	v_fmac_f32_e32 v6, v22, v7
	v_fmac_f32_e32 v6, v23, v27
	v_fmac_f32_e32 v6, v24, v29
	v_fmac_f32_e32 v6, v25, v31
	ds_bpermute_b32 v33, v9, v6
	s_waitcnt lgkmcnt(0)
	v_add_f32_e32 v6, v6, v33
	ds_bpermute_b32 v33, v10, v6
	s_waitcnt lgkmcnt(0)
	v_add_f32_e32 v6, v6, v33
	ds_bpermute_b32 v33, v11, v6
	s_waitcnt lgkmcnt(0)
	v_add_f32_e32 v6, v6, v33
	ds_bpermute_b32 v33, v12, v6
	s_waitcnt lgkmcnt(0)
	v_add_f32_e32 v6, v6, v33
	ds_bpermute_b32 v33, v13, v6
	s_waitcnt lgkmcnt(0)
	v_add_f32_e32 v6, v6, v33
	ds_bpermute_b32 v33, v16, v6
	s_waitcnt lgkmcnt(0)
	v_add_f32_e32 v6, v6, v33
	v_mul_f32_e32 v6, 0x3b000000, v6
	v_fma_f32 v19, v19, v26, -v6
	v_fma_f32 v18, v18, v32, -v6
	v_mul_f32_e32 v19, v19, v19
	v_fma_f32 v20, v20, v28, -v6
	v_fmac_f32_e32 v19, v18, v18
	v_fma_f32 v21, v21, v30, -v6
	v_fmac_f32_e32 v19, v20, v20
	v_fma_f32 v7, v22, v7, -v6
	v_fmac_f32_e32 v19, v21, v21
	v_fma_f32 v22, v23, v27, -v6
	v_fmac_f32_e32 v19, v7, v7
	v_fma_f32 v23, v24, v29, -v6
	v_fmac_f32_e32 v19, v22, v22
	v_fmac_f32_e32 v19, v23, v23
	v_fma_f32 v7, v25, v31, -v6
	v_fmac_f32_e32 v19, v7, v7
	ds_bpermute_b32 v7, v9, v19
	s_waitcnt lgkmcnt(0)
	v_add_f32_e32 v7, v19, v7
	ds_bpermute_b32 v18, v10, v7
	s_waitcnt lgkmcnt(0)
	v_add_f32_e32 v7, v7, v18
	ds_bpermute_b32 v18, v11, v7
	s_waitcnt lgkmcnt(0)
	v_add_f32_e32 v7, v7, v18
	ds_bpermute_b32 v18, v12, v7
	s_waitcnt lgkmcnt(0)
	v_add_f32_e32 v7, v7, v18
	ds_bpermute_b32 v18, v13, v7
	s_waitcnt lgkmcnt(0)
	v_add_f32_e32 v7, v7, v18
	ds_bpermute_b32 v18, v16, v7
	s_and_saveexec_b64 s[56:57], s[42:43]
	s_cbranch_execz .LBB0_764
	s_waitcnt lgkmcnt(0)
	v_add_f32_e32 v7, v7, v18
	v_fmamk_f32 v7, v7, 0x3b000000, v194
	v_mul_f32_e32 v18, 0x4b800000, v7
	v_cmp_gt_f32_e32 vcc, s95, v7
	s_nop 1
	v_cndmask_b32_e32 v7, v7, v18, vcc
	v_rsq_f32_e32 v7, v7
	s_nop 0
	v_mul_f32_e32 v18, 0x45800000, v7
	v_cndmask_b32_e32 v7, v7, v18, vcc
	ds_write_b64 v17, v[6:7] offset:40
; DI float gelu_t(float x) { return x * sigm(1.5957691216057308f * (x + 0.044715f * x * x * x)); }
; DI void prep_a_prompt(LAS unsigned char* lds, const Params& P, int l, int unit) {
;     ...
; #pragma unroll 8
;     for (int i = 0; i < 16; ++i) { const int t = wave * 16 + i; const float* p = P32 + (size_t)(row0 + t) * LDP + C_AV + lane * 8;
;         const f32x4 a = *(const f32x4*)p, bq = *(const f32x4*)(p + 4); float x[8];
; #pragma unroll
;         for (int e = 0; e < 4; ++e) { x[e] = gelu_t(a[e]); x[4 + e] = gelu_t(bq[e]); }
;         float s = 0.f;
; #pragma unroll
;         for (int e = 0; e < 8; ++e) s += x[e];
;         const float mean = wsum(s) * (1.f / 512.f); float d = 0.f;
; #pragma unroll
;         for (int e = 0; e < 8; ++e) d += (x[e] - mean) * (x[e] - mean);
;         const float var = wsum(d) * (1.f / 512.f);
;         if (lane == 0) { st[t * 2] = mean; st[t * 2 + 1] = rsqrtf(var + 1e-6f); } }
.LBB0_764:
	s_or_b64 exec, exec, s[56:57]
	s_waitcnt lgkmcnt(0)
	v_add_co_u32_e32 v18, vcc, 0x27000, v4
	s_mov_b64 s[6:7], 0x27800
	s_nop 0
	v_addc_co_u32_e32 v19, vcc, 0, v5, vcc
	v_lshl_add_u64 v[6:7], v[4:5], 0, s[6:7]
	s_nop 0
	s_waitcnt vmcnt(3)
	v_mov_b32_e32 v18, v104
	v_mov_b32_e32 v19, v105
	v_mov_b32_e32 v20, v106
	v_mov_b32_e32 v21, v107
	v_mul_f32_e32 v6, 0x3d372713, v18
	v_mul_f32_e32 v26, 0x3d372713, v19
	v_mul_f32_e32 v6, v18, v6
	v_mul_f32_e32 v28, 0x3d372713, v20
	v_mul_f32_e32 v26, v19, v26
	v_fma_f32 v6, v18, v6, v18
	v_mul_f32_e32 v30, 0x3d372713, v21
	v_mul_f32_e32 v28, v20, v28
	v_fma_f32 v26, v19, v26, v19
	v_mul_f32_e32 v6, 0x3fcc422a, v6
	s_waitcnt vmcnt(2)
	v_mov_b32_e32 v22, v108
	v_mov_b32_e32 v23, v109
	v_mov_b32_e32 v24, v110
	v_mov_b32_e32 v25, v111
	v_mul_f32_e32 v7, 0x3d372713, v22
	v_mul_f32_e32 v30, v21, v30
	v_fma_f32 v28, v20, v28, v20
	v_mul_f32_e32 v26, 0x3fcc422a, v26
	v_mul_f32_e32 v6, 0xbfb8aa3b, v6
	v_mul_f32_e32 v27, 0x3d372713, v23
	v_mul_f32_e32 v7, v22, v7
	v_fma_f32 v30, v21, v30, v21
	v_mul_f32_e32 v28, 0x3fcc422a, v28
	v_mul_f32_e32 v26, 0xbfb8aa3b, v26
	v_exp_f32_e32 v6, v6
	v_mul_f32_e32 v29, 0x3d372713, v24
	v_mul_f32_e32 v27, v23, v27
	v_fma_f32 v7, v22, v7, v22
	v_mul_f32_e32 v30, 0x3fcc422a, v30
	v_mul_f32_e32 v28, 0xbfb8aa3b, v28
	v_exp_f32_e32 v26, v26
	v_mul_f32_e32 v31, 0x3d372713, v25
	v_mul_f32_e32 v29, v24, v29
	v_fma_f32 v27, v23, v27, v23
	v_mul_f32_e32 v7, 0x3fcc422a, v7
	v_mul_f32_e32 v30, 0xbfb8aa3b, v30
	v_exp_f32_e32 v28, v28
	v_mul_f32_e32 v31, v25, v31
	v_fma_f32 v29, v24, v29, v24
	v_mul_f32_e32 v27, 0x3fcc422a, v27
	v_mul_f32_e32 v7, 0xbfb8aa3b, v7
	v_exp_f32_e32 v30, v30
	v_fma_f32 v31, v25, v31, v25
	v_mul_f32_e32 v29, 0x3fcc422a, v29
	v_mul_f32_e32 v27, 0xbfb8aa3b, v27
	v_exp_f32_e32 v7, v7
	v_add_f32_e32 v6, 1.0, v6
	v_mul_f32_e32 v31, 0x3fcc422a, v31
	v_mul_f32_e32 v29, 0xbfb8aa3b, v29
	v_exp_f32_e32 v27, v27
	v_add_f32_e32 v26, 1.0, v26
	v_rcp_f32_e32 v32, v6
	v_mul_f32_e32 v31, 0xbfb8aa3b, v31
	v_exp_f32_e32 v29, v29
	v_add_f32_e32 v28, 1.0, v28
	v_rcp_f32_e32 v26, v26
	v_exp_f32_e32 v31, v31
	v_add_f32_e32 v30, 1.0, v30
	v_rcp_f32_e32 v28, v28
	v_add_f32_e32 v7, 1.0, v7
	v_rcp_f32_e32 v30, v30
	v_add_f32_e32 v27, 1.0, v27
	v_rcp_f32_e32 v7, v7
	v_fma_f32 v6, v18, v32, 0
	v_add_f32_e32 v29, 1.0, v29
	v_rcp_f32_e32 v27, v27
	v_fmac_f32_e32 v6, v19, v26
	v_add_f32_e32 v31, 1.0, v31
	v_rcp_f32_e32 v29, v29
	v_fmac_f32_e32 v6, v20, v28
	v_rcp_f32_e32 v31, v31
	v_fmac_f32_e32 v6, v21, v30
	v_fmac_f32_e32 v6, v22, v7
	v_fmac_f32_e32 v6, v23, v27
	v_fmac_f32_e32 v6, v24, v29
	v_fmac_f32_e32 v6, v25, v31
	ds_bpermute_b32 v33, v9, v6
	s_waitcnt lgkmcnt(0)
	v_add_f32_e32 v6, v6, v33
	ds_bpermute_b32 v33, v10, v6
	s_waitcnt lgkmcnt(0)
	v_add_f32_e32 v6, v6, v33
	ds_bpermute_b32 v33, v11, v6
	s_waitcnt lgkmcnt(0)
	v_add_f32_e32 v6, v6, v33
	ds_bpermute_b32 v33, v12, v6
	s_waitcnt lgkmcnt(0)
	v_add_f32_e32 v6, v6, v33
	ds_bpermute_b32 v33, v13, v6
	s_waitcnt lgkmcnt(0)
	v_add_f32_e32 v6, v6, v33
	ds_bpermute_b32 v33, v16, v6
	s_waitcnt lgkmcnt(0)
	v_add_f32_e32 v6, v6, v33
	v_mul_f32_e32 v6, 0x3b000000, v6
	v_fma_f32 v19, v19, v26, -v6
	v_fma_f32 v18, v18, v32, -v6
	v_mul_f32_e32 v19, v19, v19
	v_fma_f32 v20, v20, v28, -v6
	v_fmac_f32_e32 v19, v18, v18
	v_fma_f32 v21, v21, v30, -v6
	v_fmac_f32_e32 v19, v20, v20
	v_fma_f32 v7, v22, v7, -v6
	v_fmac_f32_e32 v19, v21, v21
	v_fma_f32 v22, v23, v27, -v6
	v_fmac_f32_e32 v19, v7, v7
	v_fma_f32 v23, v24, v29, -v6
	v_fmac_f32_e32 v19, v22, v22
	v_fmac_f32_e32 v19, v23, v23
	v_fma_f32 v7, v25, v31, -v6
	v_fmac_f32_e32 v19, v7, v7
	ds_bpermute_b32 v7, v9, v19
	s_waitcnt lgkmcnt(0)
	v_add_f32_e32 v7, v19, v7
	ds_bpermute_b32 v18, v10, v7
	s_waitcnt lgkmcnt(0)
	v_add_f32_e32 v7, v7, v18
	ds_bpermute_b32 v18, v11, v7
	s_waitcnt lgkmcnt(0)
	v_add_f32_e32 v7, v7, v18
	ds_bpermute_b32 v18, v12, v7
	s_waitcnt lgkmcnt(0)
	v_add_f32_e32 v7, v7, v18
	ds_bpermute_b32 v18, v13, v7
	s_waitcnt lgkmcnt(0)
	v_add_f32_e32 v7, v7, v18
	ds_bpermute_b32 v18, v16, v7
	s_and_saveexec_b64 s[56:57], s[42:43]
	s_cbranch_execz .LBB0_766
	s_waitcnt lgkmcnt(0)
	v_add_f32_e32 v7, v7, v18
	v_fmamk_f32 v7, v7, 0x3b000000, v194
	v_mul_f32_e32 v18, 0x4b800000, v7
	v_cmp_gt_f32_e32 vcc, s95, v7
	s_nop 1
	v_cndmask_b32_e32 v7, v7, v18, vcc
	v_rsq_f32_e32 v7, v7
	s_nop 0
	v_mul_f32_e32 v18, 0x45800000, v7
	v_cndmask_b32_e32 v7, v7, v18, vcc
	ds_write_b64 v17, v[6:7] offset:48
; DI float gelu_t(float x) { return x * sigm(1.5957691216057308f * (x + 0.044715f * x * x * x)); }
; DI void prep_a_prompt(LAS unsigned char* lds, const Params& P, int l, int unit) {
;     ...
; #pragma unroll 8
;     for (int i = 0; i < 16; ++i) { const int t = wave * 16 + i; const float* p = P32 + (size_t)(row0 + t) * LDP + C_AV + lane * 8;
;         const f32x4 a = *(const f32x4*)p, bq = *(const f32x4*)(p + 4); float x[8];
; #pragma unroll
;         for (int e = 0; e < 4; ++e) { x[e] = gelu_t(a[e]); x[4 + e] = gelu_t(bq[e]); }
;         float s = 0.f;
; #pragma unroll
;         for (int e = 0; e < 8; ++e) s += x[e];
;         const float mean = wsum(s) * (1.f / 512.f); float d = 0.f;
; #pragma unroll
;         for (int e = 0; e < 8; ++e) d += (x[e] - mean) * (x[e] - mean);
;         const float var = wsum(d) * (1.f / 512.f);
;         if (lane == 0) { st[t * 2] = mean; st[t * 2 + 1] = rsqrtf(var + 1e-6f); } }
.LBB0_766:
	s_or_b64 exec, exec, s[56:57]
	s_mov_b64 s[6:7], 0x2e000
	v_lshl_add_u64 v[6:7], v[4:5], 0, s[6:7]
	v_add_co_u32_e32 v4, vcc, 0x2e000, v4
	s_nop 1
	v_addc_co_u32_e32 v5, vcc, 0, v5, vcc
	s_waitcnt lgkmcnt(0)
	s_waitcnt vmcnt(1)
	v_mov_b32_e32 v18, v112
	v_mov_b32_e32 v19, v113
	v_mov_b32_e32 v20, v114
	v_mov_b32_e32 v21, v115
	v_mul_f32_e32 v4, 0x3d372713, v18
	v_mul_f32_e32 v6, 0x3d372713, v19
	v_mul_f32_e32 v4, v18, v4
	v_mul_f32_e32 v26, 0x3d372713, v20
	v_mul_f32_e32 v6, v19, v6
	v_fma_f32 v4, v18, v4, v18
	v_mul_f32_e32 v28, 0x3d372713, v21
	v_mul_f32_e32 v26, v20, v26
	v_fma_f32 v6, v19, v6, v19
	v_mul_f32_e32 v4, 0x3fcc422a, v4
	s_waitcnt vmcnt(0)
	v_mov_b32_e32 v22, v116
	v_mov_b32_e32 v23, v117
	v_mov_b32_e32 v24, v118
	v_mov_b32_e32 v25, v119
	v_mul_f32_e32 v5, 0x3d372713, v22
	v_mul_f32_e32 v28, v21, v28
	v_fma_f32 v26, v20, v26, v20
	v_mul_f32_e32 v6, 0x3fcc422a, v6
	v_mul_f32_e32 v4, 0xbfb8aa3b, v4
	v_mul_f32_e32 v7, 0x3d372713, v23
	v_mul_f32_e32 v5, v22, v5
	v_fma_f32 v28, v21, v28, v21
	v_mul_f32_e32 v26, 0x3fcc422a, v26
	v_mul_f32_e32 v6, 0xbfb8aa3b, v6
	v_exp_f32_e32 v4, v4
	v_mul_f32_e32 v27, 0x3d372713, v24
	v_mul_f32_e32 v7, v23, v7
	v_fma_f32 v5, v22, v5, v22
	v_mul_f32_e32 v28, 0x3fcc422a, v28
	v_mul_f32_e32 v26, 0xbfb8aa3b, v26
	v_exp_f32_e32 v6, v6
	v_mul_f32_e32 v29, 0x3d372713, v25
	v_mul_f32_e32 v27, v24, v27
	v_fma_f32 v7, v23, v7, v23
	v_mul_f32_e32 v5, 0x3fcc422a, v5
	v_mul_f32_e32 v28, 0xbfb8aa3b, v28
	v_exp_f32_e32 v26, v26
	v_mul_f32_e32 v29, v25, v29
	v_fma_f32 v27, v24, v27, v24
	v_mul_f32_e32 v7, 0x3fcc422a, v7
	v_mul_f32_e32 v5, 0xbfb8aa3b, v5
	v_exp_f32_e32 v28, v28
	v_fma_f32 v29, v25, v29, v25
	v_mul_f32_e32 v27, 0x3fcc422a, v27
	v_mul_f32_e32 v7, 0xbfb8aa3b, v7
	v_exp_f32_e32 v5, v5
	v_add_f32_e32 v4, 1.0, v4
	v_mul_f32_e32 v29, 0x3fcc422a, v29
	v_mul_f32_e32 v27, 0xbfb8aa3b, v27
	v_exp_f32_e32 v7, v7
	v_add_f32_e32 v6, 1.0, v6
	v_rcp_f32_e32 v30, v4
	v_mul_f32_e32 v29, 0xbfb8aa3b, v29
	v_exp_f32_e32 v27, v27
	v_add_f32_e32 v26, 1.0, v26
	v_rcp_f32_e32 v6, v6
	v_exp_f32_e32 v29, v29
	v_add_f32_e32 v28, 1.0, v28
	v_rcp_f32_e32 v26, v26
	v_add_f32_e32 v5, 1.0, v5
	v_rcp_f32_e32 v28, v28
	v_add_f32_e32 v7, 1.0, v7
	v_rcp_f32_e32 v5, v5
	v_fma_f32 v4, v18, v30, 0
	v_add_f32_e32 v27, 1.0, v27
	v_rcp_f32_e32 v7, v7
	v_fmac_f32_e32 v4, v19, v6
	v_add_f32_e32 v29, 1.0, v29
	v_rcp_f32_e32 v27, v27
	v_fmac_f32_e32 v4, v20, v26
	v_rcp_f32_e32 v29, v29
	v_fmac_f32_e32 v4, v21, v28
	v_fmac_f32_e32 v4, v22, v5
	v_fmac_f32_e32 v4, v23, v7
	v_fmac_f32_e32 v4, v24, v27
	v_fmac_f32_e32 v4, v25, v29
	ds_bpermute_b32 v31, v9, v4
	s_waitcnt lgkmcnt(0)
	v_add_f32_e32 v4, v4, v31
	ds_bpermute_b32 v31, v10, v4
	s_waitcnt lgkmcnt(0)
	v_add_f32_e32 v4, v4, v31
	ds_bpermute_b32 v31, v11, v4
	s_waitcnt lgkmcnt(0)
	v_add_f32_e32 v4, v4, v31
	ds_bpermute_b32 v31, v12, v4
	s_waitcnt lgkmcnt(0)
	v_add_f32_e32 v4, v4, v31
	ds_bpermute_b32 v31, v13, v4
	s_waitcnt lgkmcnt(0)
	v_add_f32_e32 v4, v4, v31
	ds_bpermute_b32 v31, v16, v4
	s_waitcnt lgkmcnt(0)
	v_add_f32_e32 v4, v4, v31
	v_mul_f32_e32 v4, 0x3b000000, v4
	v_fma_f32 v6, v19, v6, -v4
	v_fma_f32 v18, v18, v30, -v4
	v_mul_f32_e32 v6, v6, v6
	v_fma_f32 v19, v20, v26, -v4
	v_fmac_f32_e32 v6, v18, v18
	v_fma_f32 v20, v21, v28, -v4
	v_fmac_f32_e32 v6, v19, v19
	v_fma_f32 v5, v22, v5, -v4
	v_fmac_f32_e32 v6, v20, v20
	v_fma_f32 v7, v23, v7, -v4
	v_fmac_f32_e32 v6, v5, v5
	v_fma_f32 v21, v24, v27, -v4
	v_fmac_f32_e32 v6, v7, v7
	v_fmac_f32_e32 v6, v21, v21
	v_fma_f32 v5, v25, v29, -v4
	v_fmac_f32_e32 v6, v5, v5
	ds_bpermute_b32 v5, v9, v6
	s_waitcnt lgkmcnt(0)
	v_add_f32_e32 v5, v6, v5
	ds_bpermute_b32 v6, v10, v5
	s_waitcnt lgkmcnt(0)
	v_add_f32_e32 v5, v5, v6
	ds_bpermute_b32 v6, v11, v5
	s_waitcnt lgkmcnt(0)
	v_add_f32_e32 v5, v5, v6
	ds_bpermute_b32 v6, v12, v5
	s_waitcnt lgkmcnt(0)
	v_add_f32_e32 v5, v5, v6
	ds_bpermute_b32 v6, v13, v5
	s_waitcnt lgkmcnt(0)
	v_add_f32_e32 v5, v5, v6
	ds_bpermute_b32 v6, v16, v5
	s_and_saveexec_b64 s[56:57], s[42:43]
	s_cbranch_execz .LBB0_751
	s_waitcnt lgkmcnt(0)
	v_add_f32_e32 v5, v5, v6
	v_fmamk_f32 v5, v5, 0x3b000000, v194
	v_mul_f32_e32 v6, 0x4b800000, v5
	v_cmp_gt_f32_e32 vcc, s95, v5
	s_nop 1
	v_cndmask_b32_e32 v5, v5, v6, vcc
	v_rsq_f32_e32 v5, v5
	s_nop 0
	v_mul_f32_e32 v6, 0x45800000, v5
	v_cndmask_b32_e32 v5, v5, v6, vcc
	ds_write_b64 v17, v[4:5] offset:56
	s_branch .LBB0_751
